# S5 chunk-state (ssm1) loop: 24 fragment loads per trip issued up front with counted waits
# speedup vs baseline: 1.0076x; 1.0038x over previous
.LBB0_303:
	v_lshl_add_u64 v[20:21], s[94:95], 0, v[14:15]
	v_lshl_add_u64 v[22:23], s[94:95], 0, v[16:17]
	s_mov_b64 s[98:99], 0x1400
	v_add_co_u32_e32 v134, vcc, 0x6c00200, v20
	s_nop 1
	v_addc_co_u32_e32 v135, vcc, 0, v21, vcc
	v_add_co_u32_e32 v18, vcc, 0x13a58000, v22
	s_nop 1
	v_addc_co_u32_e32 v19, vcc, 0, v23, vcc
	v_add_co_u32_e32 v22, vcc, 0x13a60000, v22
	s_nop 1
	v_addc_co_u32_e32 v23, vcc, 0, v23, vcc
	global_load_dwordx4 v[38:41], v[134:135], off
	v_lshl_add_u64 v[134:135], v[134:135], 0, s[98:99]
	global_load_dwordx4 v[70:73], v[18:19], off
	global_load_dwordx4 v[102:105], v[22:23], off
	global_load_dwordx4 v[42:45], v[134:135], off
	v_lshl_add_u64 v[134:135], v[134:135], 0, s[98:99]
	global_load_dwordx4 v[74:77], v[18:19], off offset:64
	global_load_dwordx4 v[106:109], v[22:23], off offset:64
	global_load_dwordx4 v[46:49], v[134:135], off
	v_lshl_add_u64 v[134:135], v[134:135], 0, s[98:99]
	global_load_dwordx4 v[78:81], v[18:19], off offset:128
	global_load_dwordx4 v[110:113], v[22:23], off offset:128
	global_load_dwordx4 v[50:53], v[134:135], off
	v_lshl_add_u64 v[134:135], v[134:135], 0, s[98:99]
	global_load_dwordx4 v[82:85], v[18:19], off offset:192
	global_load_dwordx4 v[114:117], v[22:23], off offset:192
	global_load_dwordx4 v[54:57], v[134:135], off
	v_lshl_add_u64 v[134:135], v[134:135], 0, s[98:99]
	global_load_dwordx4 v[86:89], v[18:19], off offset:256
	global_load_dwordx4 v[118:121], v[22:23], off offset:256
	global_load_dwordx4 v[58:61], v[134:135], off
	v_lshl_add_u64 v[134:135], v[134:135], 0, s[98:99]
	global_load_dwordx4 v[90:93], v[18:19], off offset:320
	global_load_dwordx4 v[122:125], v[22:23], off offset:320
	global_load_dwordx4 v[62:65], v[134:135], off
	v_lshl_add_u64 v[134:135], v[134:135], 0, s[98:99]
	global_load_dwordx4 v[94:97], v[18:19], off offset:384
	global_load_dwordx4 v[126:129], v[22:23], off offset:384
	global_load_dwordx4 v[66:69], v[134:135], off
	v_lshl_add_u64 v[134:135], v[134:135], 0, s[98:99]
	global_load_dwordx4 v[98:101], v[18:19], off offset:448
	global_load_dwordx4 v[130:133], v[22:23], off offset:448
	s_mov_b64 s[0:1], 0xa000
	v_lshl_add_u64 v[14:15], v[14:15], 0, s[0:1]
	s_mov_b64 s[0:1], 0x200
	s_add_i32 s19, s19, -8
	v_lshl_add_u64 v[16:17], v[16:17], 0, s[0:1]
	s_cmp_lg_u32 s19, 0
	s_waitcnt vmcnt(21)
	v_mfma_f32_16x16x32_bf16 v[2:5], v[70:73], v[38:41], v[2:5]
	v_mfma_f32_16x16x32_bf16 v[6:9], v[102:105], v[38:41], v[6:9]
	s_waitcnt vmcnt(18)
	v_mfma_f32_16x16x32_bf16 v[2:5], v[74:77], v[42:45], v[2:5]
	v_mfma_f32_16x16x32_bf16 v[6:9], v[106:109], v[42:45], v[6:9]
	s_waitcnt vmcnt(15)
	v_mfma_f32_16x16x32_bf16 v[2:5], v[78:81], v[46:49], v[2:5]
	v_mfma_f32_16x16x32_bf16 v[6:9], v[110:113], v[46:49], v[6:9]
	s_waitcnt vmcnt(12)
	v_mfma_f32_16x16x32_bf16 v[2:5], v[82:85], v[50:53], v[2:5]
	v_mfma_f32_16x16x32_bf16 v[6:9], v[114:117], v[50:53], v[6:9]
	s_waitcnt vmcnt(9)
	v_mfma_f32_16x16x32_bf16 v[2:5], v[86:89], v[54:57], v[2:5]
	v_mfma_f32_16x16x32_bf16 v[6:9], v[118:121], v[54:57], v[6:9]
	s_waitcnt vmcnt(6)
	v_mfma_f32_16x16x32_bf16 v[2:5], v[90:93], v[58:61], v[2:5]
	v_mfma_f32_16x16x32_bf16 v[6:9], v[122:125], v[58:61], v[6:9]
	s_waitcnt vmcnt(3)
	v_mfma_f32_16x16x32_bf16 v[2:5], v[94:97], v[62:65], v[2:5]
	v_mfma_f32_16x16x32_bf16 v[6:9], v[126:129], v[62:65], v[6:9]
	s_waitcnt vmcnt(0)
	v_mfma_f32_16x16x32_bf16 v[2:5], v[98:101], v[66:69], v[2:5]
	v_mfma_f32_16x16x32_bf16 v[6:9], v[130:133], v[66:69], v[6:9]
	s_cbranch_scc1 .LBB0_303
	v_lshl_add_u32 v0, v11, 5, s3
	v_or_b32_e32 v0, s2, v0
	v_ashrrev_i32_e32 v11, 31, v10
	v_mad_i64_i32 v[10:11], s[0:1], v0, 36, v[10:11]
	v_readlane_b32 s0, v253, 40
	v_lshlrev_b64 v[10:11], 9, v[10:11]
	v_readlane_b32 s1, v253, 41
	v_ashrrev_i32_e32 v13, 31, v12
	v_lshlrev_b32_e32 v0, 4, v24
	v_lshl_add_u64 v[10:11], s[0:1], 0, v[10:11]
	v_lshl_add_u64 v[10:11], v[12:13], 2, v[10:11]
	v_lshl_add_u64 v[10:11], v[10:11], 0, v[0:1]
	s_mov_b64 s[34:35], 0
	global_store_dwordx4 v[10:11], v[2:5], off
	global_store_dwordx4 v[10:11], v[6:9], off offset:64
